# indexer: interleaved branch-free scan loop, histogram + DPP threshold search for in-loop compaction (exact bit search kept as fallback)
# speedup vs baseline: 1.0353x; 1.0136x over previous
; __device__ __forceinline__ void dsa_wave(const Params& p, int rank, char* sm) {
;     ...
;   Tg[0] = Tg[1] = Tg[2] = Tg[3] = 0u; Tq = 0u; cntv = 0;
;   Tf[0] = Tf[1] = Tf[2] = Tf[3] = -__builtin_inff();
;   const int ntile = (l0 + 7) / 32 + 1;
;   const bf* kif = p.KIF + (size_t)b * 512 * 2048 + lane * 8;
;   bf16x8 bqA[4][4], bqB[4][4];
; #pragma unroll
;   for (int s = 0; s < 4; s++) {
;     const int ts = s < ntile ? s : ntile - 1;
; #pragma unroll
;     for (int ks = 0; ks < 4; ks++) bqA[s][ks] = *(const bf16x8*)(kif + (size_t)ts * 2048 + ks * 512);
;   }
;   const unsigned ltmask = (1u << r32) - 1u;
.LBB0_543:
	v_mov_b32_e32 v144, 0
	v_mov_b32_e32 v173, 0
	s_and_saveexec_b64 s[42:43], s[6:7]
	s_cbranch_execz .LBB0_1451
	v_mov_b32_e32 v216, 0
	v_mov_b32_e32 v218, 0
	v_mov_b32_e32 v220, 0
	v_mov_b32_e32 v222, 0
	v_mov_b32_e32 v217, 0xff800000
	v_mov_b32_e32 v219, 0xff800000
	v_mov_b32_e32 v221, 0xff800000
	v_mov_b32_e32 v223, 0xff800000
	v_mov_b32_e32 v144, 0
	v_mov_b32_e32 v173, 0
	v_mov_b32_e32 v128, 0
	v_mov_b32_e32 v129, 0
	v_mov_b32_e32 v130, 0
	v_mov_b32_e32 v131, 0
	v_mov_b32_e32 v132, 0
	v_mov_b32_e32 v133, 0
	v_mov_b32_e32 v134, 0
	v_mov_b32_e32 v135, 0
	v_lshlrev_b32_e32 v11, 4, v151
	v_add_u32_e32 v137, 0x1000, v214
	v_add_u32_e32 v138, 0x2000, v214
	v_add_u32_e32 v139, 0x3000, v214
	v_lshlrev_b32_e32 v224, 12, v155
	v_add_u32_e32 v224, s77, v224
	v_lshl_add_u32 v136, v151, 2, v224
	v_readfirstlane_b32 s61, v189
	v_readfirstlane_b32 s66, v150
	v_readfirstlane_b32 s62, v203
	v_readlane_b32 s64, v253, 22
	v_readlane_b32 s65, v253, 23
	s_bfe_u32 s62, s62, 0x10006
	s_lshl_b32 s62, s62, 21
	s_add_u32 s64, s64, s62
	s_addc_u32 s65, s65, 0
	s_mov_b32 s60, 0
	s_min_u32 s62, 0, s61
	s_lshl_b32 s62, s62, 12
	v_add_u32_e32 v14, s62, v11
	global_load_dwordx4 v[32:35], v14, s[64:65]
	global_load_dwordx4 v[36:39], v14, s[64:65] offset:1024
	global_load_dwordx4 v[40:43], v14, s[64:65] offset:2048
	global_load_dwordx4 v[44:47], v14, s[64:65] offset:3072
	s_min_u32 s62, 1, s61
	s_lshl_b32 s62, s62, 12
	v_add_u32_e32 v14, s62, v11
	global_load_dwordx4 v[48:51], v14, s[64:65]
	global_load_dwordx4 v[52:55], v14, s[64:65] offset:1024
	global_load_dwordx4 v[56:59], v14, s[64:65] offset:2048
	global_load_dwordx4 v[60:63], v14, s[64:65] offset:3072
	s_min_u32 s62, 2, s61
	s_lshl_b32 s62, s62, 12
	v_add_u32_e32 v14, s62, v11
	global_load_dwordx4 v[64:67], v14, s[64:65]
	global_load_dwordx4 v[68:71], v14, s[64:65] offset:1024
	global_load_dwordx4 v[72:75], v14, s[64:65] offset:2048
	global_load_dwordx4 v[76:79], v14, s[64:65] offset:3072
	s_waitcnt vmcnt(8)
	v_mfma_f32_32x32x16_bf16 v[96:111], v[24:27], v[32:35], 0
	v_mfma_f32_32x32x16_bf16 v[96:111], v[16:19], v[36:39], v[96:111]
	v_mfma_f32_32x32x16_bf16 v[96:111], v[20:23], v[40:43], v[96:111]
	v_mfma_f32_32x32x16_bf16 v[96:111], v[28:31], v[44:47], v[96:111]
.Lidx_loop:
.Lidx_tile0:
	s_add_u32 s62, s60, 3
	s_min_u32 s62, s62, s61
	s_lshl_b32 s62, s62, 12
	v_add_u32_e32 v14, s62, v11
	global_load_dwordx4 v[80:83], v14, s[64:65]
	global_load_dwordx4 v[84:87], v14, s[64:65] offset:1024
	global_load_dwordx4 v[88:91], v14, s[64:65] offset:2048
	global_load_dwordx4 v[92:95], v14, s[64:65] offset:3072
	v_max3_u32 v15, v128, v129, v130
	v_max3_u32 v15, v15, v131, v132
	v_max3_u32 v15, v15, v133, v134
	v_max_u32_e32 v15, v15, v135
	v_cmp_lt_u32_e32 vcc, s80, v15
	s_cbranch_vccnz .Lidx_compact0
.Lidx_resume0:
	s_waitcnt vmcnt(8)
	v_mfma_f32_32x32x16_bf16 v[112:127], v[24:27], v[48:51], 0
	v_mfma_f32_32x32x16_bf16 v[112:127], v[16:19], v[52:55], v[112:127]
	v_mfma_f32_32x32x16_bf16 v[112:127], v[20:23], v[56:59], v[112:127]
	v_mfma_f32_32x32x16_bf16 v[112:127], v[28:31], v[60:63], v[112:127]
	s_lshl_b32 s62, s60, 5
	v_add_u32_e32 v215, s62, v157
	v_sub_u32_e32 v13, 0x3fff, v215
	s_add_u32 s62, s62, 31
	s_cmp_gt_u32 s62, s66
	s_cbranch_scc1 .Lidx_diag0
	v_max_i32_e32 v96, 0, v96
	v_max_i32_e32 v100, 0, v100
	v_max_i32_e32 v104, 0, v104
	v_max_i32_e32 v108, 0, v108
	v_max_i32_e32 v97, 0, v97
	v_max_i32_e32 v101, 0, v101
	v_max_i32_e32 v105, 0, v105
	v_max_i32_e32 v109, 0, v109
	v_mul_f32_e32 v96, v159, v96
	v_mul_f32_e32 v100, v177, v100
	v_mul_f32_e32 v104, v181, v104
	v_mul_f32_e32 v108, v185, v108
	v_max_i32_e32 v98, 0, v98
	v_max_i32_e32 v102, 0, v102
	v_max_i32_e32 v106, 0, v106
	v_max_i32_e32 v110, 0, v110
	v_fmac_f32_e32 v96, v97, v174
	v_fmac_f32_e32 v100, v101, v178
	v_fmac_f32_e32 v104, v105, v182
	v_fmac_f32_e32 v108, v109, v186
	v_max_i32_e32 v99, 0, v99
	v_max_i32_e32 v103, 0, v103
	v_max_i32_e32 v107, 0, v107
	v_max_i32_e32 v111, 0, v111
	v_fmac_f32_e32 v96, v98, v175
	v_fmac_f32_e32 v100, v102, v179
	v_fmac_f32_e32 v104, v106, v183
	v_fmac_f32_e32 v108, v110, v187
	v_fmac_f32_e32 v96, v99, v176
	v_fmac_f32_e32 v100, v103, v180
	v_fmac_f32_e32 v104, v107, v184
	v_fmac_f32_e32 v108, v111, v188
	v_add_f32_e32 v96, 0, v96
	v_add_f32_e32 v100, 0, v100
	v_add_f32_e32 v104, 0, v104
	v_add_f32_e32 v108, 0, v108
	v_ashrrev_i32_e32 v97, 31, v96
	v_ashrrev_i32_e32 v101, 31, v100
	v_ashrrev_i32_e32 v105, 31, v104
	v_ashrrev_i32_e32 v109, 31, v108
	v_bitop3_b32 v96, v97, v96, s81 bitop3:0x36
	v_bitop3_b32 v100, v101, v100, s81 bitop3:0x36
	v_bitop3_b32 v104, v105, v104, s81 bitop3:0x36
	v_bitop3_b32 v108, v109, v108, s81 bitop3:0x36
	v_and_or_b32 v96, v96, s82, v13
	v_and_or_b32 v100, v100, s82, v13
	v_and_or_b32 v104, v104, s82, v13
	v_and_or_b32 v108, v108, s82, v13
	v_cmp_ge_u32_e64 s[26:27], v96, v216
	v_cmp_ge_u32_e64 s[28:29], v100, v218
	v_cmp_ge_u32_e64 s[30:31], v104, v220
	v_cmp_ge_u32_e64 s[34:35], v108, v222
	v_cndmask_b32_e64 v97, v129, v128, s[4:5]
	v_cndmask_b32_e64 v101, v131, v130, s[4:5]
	v_cndmask_b32_e64 v105, v133, v132, s[4:5]
	v_cndmask_b32_e64 v109, v135, v134, s[4:5]
	v_mbcnt_lo_u32_b32 v98, s26, 0
	v_mbcnt_lo_u32_b32 v102, s28, 0
	v_mbcnt_lo_u32_b32 v106, s30, 0
	v_mbcnt_lo_u32_b32 v110, s34, 0
	v_mbcnt_hi_u32_b32 v99, s27, 0
	v_mbcnt_hi_u32_b32 v103, s29, 0
	v_mbcnt_hi_u32_b32 v107, s31, 0
	v_mbcnt_hi_u32_b32 v111, s35, 0
	v_cndmask_b32_e64 v98, v99, v98, s[4:5]
	v_cndmask_b32_e64 v102, v103, v102, s[4:5]
	v_cndmask_b32_e64 v106, v107, v106, s[4:5]
	v_cndmask_b32_e64 v110, v111, v110, s[4:5]
	v_add_u32_e32 v97, v97, v98
	v_add_u32_e32 v101, v101, v102
	v_add_u32_e32 v105, v105, v106
	v_add_u32_e32 v109, v109, v110
	v_lshl_add_u32 v97, v97, 2, v214
	v_lshl_add_u32 v101, v101, 2, v137
	v_lshl_add_u32 v105, v105, 2, v138
	v_lshl_add_u32 v109, v109, 2, v139
	v_cndmask_b32_e64 v97, v136, v97, s[26:27]
	v_cndmask_b32_e64 v101, v136, v101, s[28:29]
	v_cndmask_b32_e64 v105, v136, v105, s[30:31]
	v_cndmask_b32_e64 v109, v136, v109, s[34:35]
	ds_write_b32 v97, v96
	ds_write_b32 v101, v100
	ds_write_b32 v105, v104
	ds_write_b32 v109, v108
	v_bcnt_u32_b32 v128, s26, v128
	v_bcnt_u32_b32 v130, s28, v130
	v_bcnt_u32_b32 v132, s30, v132
	v_bcnt_u32_b32 v134, s34, v134
	v_bcnt_u32_b32 v129, s27, v129
	v_bcnt_u32_b32 v131, s29, v131
	v_bcnt_u32_b32 v133, s31, v133
	v_bcnt_u32_b32 v135, s35, v135
.Lidx_next0:
	s_add_u32 s60, s60, 1
	s_cmp_gt_u32 s60, s61
	s_cbranch_scc1 .Lidx_done
.Lidx_tile1:
	s_add_u32 s62, s60, 3
	s_min_u32 s62, s62, s61
	s_lshl_b32 s62, s62, 12
	v_add_u32_e32 v14, s62, v11
	global_load_dwordx4 v[32:35], v14, s[64:65]
	global_load_dwordx4 v[36:39], v14, s[64:65] offset:1024
	global_load_dwordx4 v[40:43], v14, s[64:65] offset:2048
	global_load_dwordx4 v[44:47], v14, s[64:65] offset:3072
	v_max3_u32 v15, v128, v129, v130
	v_max3_u32 v15, v15, v131, v132
	v_max3_u32 v15, v15, v133, v134
	v_max_u32_e32 v15, v15, v135
	v_cmp_lt_u32_e32 vcc, s80, v15
	s_cbranch_vccnz .Lidx_compact1
.Lidx_resume1:
	s_waitcnt vmcnt(8)
	v_mfma_f32_32x32x16_bf16 v[96:111], v[24:27], v[64:67], 0
	v_mfma_f32_32x32x16_bf16 v[96:111], v[16:19], v[68:71], v[96:111]
	v_mfma_f32_32x32x16_bf16 v[96:111], v[20:23], v[72:75], v[96:111]
	v_mfma_f32_32x32x16_bf16 v[96:111], v[28:31], v[76:79], v[96:111]
	s_lshl_b32 s62, s60, 5
	v_add_u32_e32 v215, s62, v157
	v_sub_u32_e32 v13, 0x3fff, v215
	s_add_u32 s62, s62, 31
	s_cmp_gt_u32 s62, s66
	s_cbranch_scc1 .Lidx_diag1
	v_max_i32_e32 v112, 0, v112
	v_max_i32_e32 v116, 0, v116
	v_max_i32_e32 v120, 0, v120
	v_max_i32_e32 v124, 0, v124
	v_max_i32_e32 v113, 0, v113
	v_max_i32_e32 v117, 0, v117
	v_max_i32_e32 v121, 0, v121
	v_max_i32_e32 v125, 0, v125
	v_mul_f32_e32 v112, v159, v112
	v_mul_f32_e32 v116, v177, v116
	v_mul_f32_e32 v120, v181, v120
	v_mul_f32_e32 v124, v185, v124
	v_max_i32_e32 v114, 0, v114
	v_max_i32_e32 v118, 0, v118
	v_max_i32_e32 v122, 0, v122
	v_max_i32_e32 v126, 0, v126
	v_fmac_f32_e32 v112, v113, v174
	v_fmac_f32_e32 v116, v117, v178
	v_fmac_f32_e32 v120, v121, v182
	v_fmac_f32_e32 v124, v125, v186
	v_max_i32_e32 v115, 0, v115
	v_max_i32_e32 v119, 0, v119
	v_max_i32_e32 v123, 0, v123
	v_max_i32_e32 v127, 0, v127
	v_fmac_f32_e32 v112, v114, v175
	v_fmac_f32_e32 v116, v118, v179
	v_fmac_f32_e32 v120, v122, v183
	v_fmac_f32_e32 v124, v126, v187
	v_fmac_f32_e32 v112, v115, v176
	v_fmac_f32_e32 v116, v119, v180
	v_fmac_f32_e32 v120, v123, v184
	v_fmac_f32_e32 v124, v127, v188
	v_add_f32_e32 v112, 0, v112
	v_add_f32_e32 v116, 0, v116
	v_add_f32_e32 v120, 0, v120
	v_add_f32_e32 v124, 0, v124
	v_ashrrev_i32_e32 v113, 31, v112
	v_ashrrev_i32_e32 v117, 31, v116
	v_ashrrev_i32_e32 v121, 31, v120
	v_ashrrev_i32_e32 v125, 31, v124
	v_bitop3_b32 v112, v113, v112, s81 bitop3:0x36
	v_bitop3_b32 v116, v117, v116, s81 bitop3:0x36
	v_bitop3_b32 v120, v121, v120, s81 bitop3:0x36
	v_bitop3_b32 v124, v125, v124, s81 bitop3:0x36
	v_and_or_b32 v112, v112, s82, v13
	v_and_or_b32 v116, v116, s82, v13
	v_and_or_b32 v120, v120, s82, v13
	v_and_or_b32 v124, v124, s82, v13
	v_cmp_ge_u32_e64 s[26:27], v112, v216
	v_cmp_ge_u32_e64 s[28:29], v116, v218
	v_cmp_ge_u32_e64 s[30:31], v120, v220
	v_cmp_ge_u32_e64 s[34:35], v124, v222
	v_cndmask_b32_e64 v113, v129, v128, s[4:5]
	v_cndmask_b32_e64 v117, v131, v130, s[4:5]
	v_cndmask_b32_e64 v121, v133, v132, s[4:5]
	v_cndmask_b32_e64 v125, v135, v134, s[4:5]
	v_mbcnt_lo_u32_b32 v114, s26, 0
	v_mbcnt_lo_u32_b32 v118, s28, 0
	v_mbcnt_lo_u32_b32 v122, s30, 0
	v_mbcnt_lo_u32_b32 v126, s34, 0
	v_mbcnt_hi_u32_b32 v115, s27, 0
	v_mbcnt_hi_u32_b32 v119, s29, 0
	v_mbcnt_hi_u32_b32 v123, s31, 0
	v_mbcnt_hi_u32_b32 v127, s35, 0
	v_cndmask_b32_e64 v114, v115, v114, s[4:5]
	v_cndmask_b32_e64 v118, v119, v118, s[4:5]
	v_cndmask_b32_e64 v122, v123, v122, s[4:5]
	v_cndmask_b32_e64 v126, v127, v126, s[4:5]
	v_add_u32_e32 v113, v113, v114
	v_add_u32_e32 v117, v117, v118
	v_add_u32_e32 v121, v121, v122
	v_add_u32_e32 v125, v125, v126
	v_lshl_add_u32 v113, v113, 2, v214
	v_lshl_add_u32 v117, v117, 2, v137
	v_lshl_add_u32 v121, v121, 2, v138
	v_lshl_add_u32 v125, v125, 2, v139
	v_cndmask_b32_e64 v113, v136, v113, s[26:27]
	v_cndmask_b32_e64 v117, v136, v117, s[28:29]
	v_cndmask_b32_e64 v121, v136, v121, s[30:31]
	v_cndmask_b32_e64 v125, v136, v125, s[34:35]
	ds_write_b32 v113, v112
	ds_write_b32 v117, v116
	ds_write_b32 v121, v120
	ds_write_b32 v125, v124
	v_bcnt_u32_b32 v128, s26, v128
	v_bcnt_u32_b32 v130, s28, v130
	v_bcnt_u32_b32 v132, s30, v132
	v_bcnt_u32_b32 v134, s34, v134
	v_bcnt_u32_b32 v129, s27, v129
	v_bcnt_u32_b32 v131, s29, v131
	v_bcnt_u32_b32 v133, s31, v133
	v_bcnt_u32_b32 v135, s35, v135

.Lidx_tile2:
	s_add_u32 s62, s60, 3
	s_min_u32 s62, s62, s61
	s_lshl_b32 s62, s62, 12
	v_add_u32_e32 v14, s62, v11
	global_load_dwordx4 v[48:51], v14, s[64:65]
	global_load_dwordx4 v[52:55], v14, s[64:65] offset:1024
	global_load_dwordx4 v[56:59], v14, s[64:65] offset:2048
	global_load_dwordx4 v[60:63], v14, s[64:65] offset:3072
	v_max3_u32 v15, v128, v129, v130
	v_max3_u32 v15, v15, v131, v132
	v_max3_u32 v15, v15, v133, v134
	v_max_u32_e32 v15, v15, v135
	v_cmp_lt_u32_e32 vcc, s80, v15
	s_cbranch_vccnz .Lidx_compact2
.Lidx_resume2:
	s_waitcnt vmcnt(8)
	v_mfma_f32_32x32x16_bf16 v[112:127], v[24:27], v[80:83], 0
	v_mfma_f32_32x32x16_bf16 v[112:127], v[16:19], v[84:87], v[112:127]
	v_mfma_f32_32x32x16_bf16 v[112:127], v[20:23], v[88:91], v[112:127]
	v_mfma_f32_32x32x16_bf16 v[112:127], v[28:31], v[92:95], v[112:127]
	s_lshl_b32 s62, s60, 5
	v_add_u32_e32 v215, s62, v157
	v_sub_u32_e32 v13, 0x3fff, v215
	s_add_u32 s62, s62, 31
	s_cmp_gt_u32 s62, s66
	s_cbranch_scc1 .Lidx_diag2
	v_max_i32_e32 v96, 0, v96
	v_max_i32_e32 v100, 0, v100
	v_max_i32_e32 v104, 0, v104
	v_max_i32_e32 v108, 0, v108
	v_max_i32_e32 v97, 0, v97
	v_max_i32_e32 v101, 0, v101
	v_max_i32_e32 v105, 0, v105
	v_max_i32_e32 v109, 0, v109
	v_mul_f32_e32 v96, v159, v96
	v_mul_f32_e32 v100, v177, v100
	v_mul_f32_e32 v104, v181, v104
	v_mul_f32_e32 v108, v185, v108
	v_max_i32_e32 v98, 0, v98
	v_max_i32_e32 v102, 0, v102
	v_max_i32_e32 v106, 0, v106
	v_max_i32_e32 v110, 0, v110
	v_fmac_f32_e32 v96, v97, v174
	v_fmac_f32_e32 v100, v101, v178
	v_fmac_f32_e32 v104, v105, v182
	v_fmac_f32_e32 v108, v109, v186
	v_max_i32_e32 v99, 0, v99
	v_max_i32_e32 v103, 0, v103
	v_max_i32_e32 v107, 0, v107
	v_max_i32_e32 v111, 0, v111
	v_fmac_f32_e32 v96, v98, v175
	v_fmac_f32_e32 v100, v102, v179
	v_fmac_f32_e32 v104, v106, v183
	v_fmac_f32_e32 v108, v110, v187
	v_fmac_f32_e32 v96, v99, v176
	v_fmac_f32_e32 v100, v103, v180
	v_fmac_f32_e32 v104, v107, v184
	v_fmac_f32_e32 v108, v111, v188
	v_add_f32_e32 v96, 0, v96
	v_add_f32_e32 v100, 0, v100
	v_add_f32_e32 v104, 0, v104
	v_add_f32_e32 v108, 0, v108
	v_ashrrev_i32_e32 v97, 31, v96
	v_ashrrev_i32_e32 v101, 31, v100
	v_ashrrev_i32_e32 v105, 31, v104
	v_ashrrev_i32_e32 v109, 31, v108
	v_bitop3_b32 v96, v97, v96, s81 bitop3:0x36
	v_bitop3_b32 v100, v101, v100, s81 bitop3:0x36
	v_bitop3_b32 v104, v105, v104, s81 bitop3:0x36
	v_bitop3_b32 v108, v109, v108, s81 bitop3:0x36
	v_and_or_b32 v96, v96, s82, v13
	v_and_or_b32 v100, v100, s82, v13
	v_and_or_b32 v104, v104, s82, v13
	v_and_or_b32 v108, v108, s82, v13
	v_cmp_ge_u32_e64 s[26:27], v96, v216
	v_cmp_ge_u32_e64 s[28:29], v100, v218
	v_cmp_ge_u32_e64 s[30:31], v104, v220
	v_cmp_ge_u32_e64 s[34:35], v108, v222
	v_cndmask_b32_e64 v97, v129, v128, s[4:5]
	v_cndmask_b32_e64 v101, v131, v130, s[4:5]
	v_cndmask_b32_e64 v105, v133, v132, s[4:5]
	v_cndmask_b32_e64 v109, v135, v134, s[4:5]
	v_mbcnt_lo_u32_b32 v98, s26, 0
	v_mbcnt_lo_u32_b32 v102, s28, 0
	v_mbcnt_lo_u32_b32 v106, s30, 0
	v_mbcnt_lo_u32_b32 v110, s34, 0
	v_mbcnt_hi_u32_b32 v99, s27, 0
	v_mbcnt_hi_u32_b32 v103, s29, 0
	v_mbcnt_hi_u32_b32 v107, s31, 0
	v_mbcnt_hi_u32_b32 v111, s35, 0
	v_cndmask_b32_e64 v98, v99, v98, s[4:5]
	v_cndmask_b32_e64 v102, v103, v102, s[4:5]
	v_cndmask_b32_e64 v106, v107, v106, s[4:5]
	v_cndmask_b32_e64 v110, v111, v110, s[4:5]
	v_add_u32_e32 v97, v97, v98
	v_add_u32_e32 v101, v101, v102
	v_add_u32_e32 v105, v105, v106
	v_add_u32_e32 v109, v109, v110
	v_lshl_add_u32 v97, v97, 2, v214
	v_lshl_add_u32 v101, v101, 2, v137
	v_lshl_add_u32 v105, v105, 2, v138
	v_lshl_add_u32 v109, v109, 2, v139
	v_cndmask_b32_e64 v97, v136, v97, s[26:27]
	v_cndmask_b32_e64 v101, v136, v101, s[28:29]
	v_cndmask_b32_e64 v105, v136, v105, s[30:31]
	v_cndmask_b32_e64 v109, v136, v109, s[34:35]
	ds_write_b32 v97, v96
	ds_write_b32 v101, v100
	ds_write_b32 v105, v104
	ds_write_b32 v109, v108
	v_bcnt_u32_b32 v128, s26, v128
	v_bcnt_u32_b32 v130, s28, v130
	v_bcnt_u32_b32 v132, s30, v132
	v_bcnt_u32_b32 v134, s34, v134
	v_bcnt_u32_b32 v129, s27, v129
	v_bcnt_u32_b32 v131, s29, v131
	v_bcnt_u32_b32 v133, s31, v133
	v_bcnt_u32_b32 v135, s35, v135

.Lidx_tile3:
	s_add_u32 s62, s60, 3
	s_min_u32 s62, s62, s61
	s_lshl_b32 s62, s62, 12
	v_add_u32_e32 v14, s62, v11
	global_load_dwordx4 v[64:67], v14, s[64:65]
	global_load_dwordx4 v[68:71], v14, s[64:65] offset:1024
	global_load_dwordx4 v[72:75], v14, s[64:65] offset:2048
	global_load_dwordx4 v[76:79], v14, s[64:65] offset:3072
	v_max3_u32 v15, v128, v129, v130
	v_max3_u32 v15, v15, v131, v132
	v_max3_u32 v15, v15, v133, v134
	v_max_u32_e32 v15, v15, v135
	v_cmp_lt_u32_e32 vcc, s80, v15
	s_cbranch_vccnz .Lidx_compact3
.Lidx_resume3:
	s_waitcnt vmcnt(8)
	v_mfma_f32_32x32x16_bf16 v[96:111], v[24:27], v[32:35], 0
	v_mfma_f32_32x32x16_bf16 v[96:111], v[16:19], v[36:39], v[96:111]
	v_mfma_f32_32x32x16_bf16 v[96:111], v[20:23], v[40:43], v[96:111]
	v_mfma_f32_32x32x16_bf16 v[96:111], v[28:31], v[44:47], v[96:111]
	s_lshl_b32 s62, s60, 5
	v_add_u32_e32 v215, s62, v157
	v_sub_u32_e32 v13, 0x3fff, v215
	s_add_u32 s62, s62, 31
	s_cmp_gt_u32 s62, s66
	s_cbranch_scc1 .Lidx_diag3
	v_max_i32_e32 v112, 0, v112
	v_max_i32_e32 v116, 0, v116
	v_max_i32_e32 v120, 0, v120
	v_max_i32_e32 v124, 0, v124
	v_max_i32_e32 v113, 0, v113
	v_max_i32_e32 v117, 0, v117
	v_max_i32_e32 v121, 0, v121
	v_max_i32_e32 v125, 0, v125
	v_mul_f32_e32 v112, v159, v112
	v_mul_f32_e32 v116, v177, v116
	v_mul_f32_e32 v120, v181, v120
	v_mul_f32_e32 v124, v185, v124
	v_max_i32_e32 v114, 0, v114
	v_max_i32_e32 v118, 0, v118
	v_max_i32_e32 v122, 0, v122
	v_max_i32_e32 v126, 0, v126
	v_fmac_f32_e32 v112, v113, v174
	v_fmac_f32_e32 v116, v117, v178
	v_fmac_f32_e32 v120, v121, v182
	v_fmac_f32_e32 v124, v125, v186
	v_max_i32_e32 v115, 0, v115
	v_max_i32_e32 v119, 0, v119
	v_max_i32_e32 v123, 0, v123
	v_max_i32_e32 v127, 0, v127
	v_fmac_f32_e32 v112, v114, v175
	v_fmac_f32_e32 v116, v118, v179
	v_fmac_f32_e32 v120, v122, v183
	v_fmac_f32_e32 v124, v126, v187
	v_fmac_f32_e32 v112, v115, v176
	v_fmac_f32_e32 v116, v119, v180
	v_fmac_f32_e32 v120, v123, v184
	v_fmac_f32_e32 v124, v127, v188
	v_add_f32_e32 v112, 0, v112
	v_add_f32_e32 v116, 0, v116
	v_add_f32_e32 v120, 0, v120
	v_add_f32_e32 v124, 0, v124
	v_ashrrev_i32_e32 v113, 31, v112
	v_ashrrev_i32_e32 v117, 31, v116
	v_ashrrev_i32_e32 v121, 31, v120
	v_ashrrev_i32_e32 v125, 31, v124
	v_bitop3_b32 v112, v113, v112, s81 bitop3:0x36
	v_bitop3_b32 v116, v117, v116, s81 bitop3:0x36
	v_bitop3_b32 v120, v121, v120, s81 bitop3:0x36
	v_bitop3_b32 v124, v125, v124, s81 bitop3:0x36
	v_and_or_b32 v112, v112, s82, v13
	v_and_or_b32 v116, v116, s82, v13
	v_and_or_b32 v120, v120, s82, v13
	v_and_or_b32 v124, v124, s82, v13
	v_cmp_ge_u32_e64 s[26:27], v112, v216
	v_cmp_ge_u32_e64 s[28:29], v116, v218
	v_cmp_ge_u32_e64 s[30:31], v120, v220
	v_cmp_ge_u32_e64 s[34:35], v124, v222
	v_cndmask_b32_e64 v113, v129, v128, s[4:5]
	v_cndmask_b32_e64 v117, v131, v130, s[4:5]
	v_cndmask_b32_e64 v121, v133, v132, s[4:5]
	v_cndmask_b32_e64 v125, v135, v134, s[4:5]
	v_mbcnt_lo_u32_b32 v114, s26, 0
	v_mbcnt_lo_u32_b32 v118, s28, 0
	v_mbcnt_lo_u32_b32 v122, s30, 0
	v_mbcnt_lo_u32_b32 v126, s34, 0
	v_mbcnt_hi_u32_b32 v115, s27, 0
	v_mbcnt_hi_u32_b32 v119, s29, 0
	v_mbcnt_hi_u32_b32 v123, s31, 0
	v_mbcnt_hi_u32_b32 v127, s35, 0
	v_cndmask_b32_e64 v114, v115, v114, s[4:5]
	v_cndmask_b32_e64 v118, v119, v118, s[4:5]
	v_cndmask_b32_e64 v122, v123, v122, s[4:5]
	v_cndmask_b32_e64 v126, v127, v126, s[4:5]
	v_add_u32_e32 v113, v113, v114
	v_add_u32_e32 v117, v117, v118
	v_add_u32_e32 v121, v121, v122
	v_add_u32_e32 v125, v125, v126
	v_lshl_add_u32 v113, v113, 2, v214
	v_lshl_add_u32 v117, v117, 2, v137
	v_lshl_add_u32 v121, v121, 2, v138
	v_lshl_add_u32 v125, v125, 2, v139
	v_cndmask_b32_e64 v113, v136, v113, s[26:27]
	v_cndmask_b32_e64 v117, v136, v117, s[28:29]
	v_cndmask_b32_e64 v121, v136, v121, s[30:31]
	v_cndmask_b32_e64 v125, v136, v125, s[34:35]
	ds_write_b32 v113, v112
	ds_write_b32 v117, v116
	ds_write_b32 v121, v120
	ds_write_b32 v125, v124
	v_bcnt_u32_b32 v128, s26, v128
	v_bcnt_u32_b32 v130, s28, v130
	v_bcnt_u32_b32 v132, s30, v132
	v_bcnt_u32_b32 v134, s34, v134
	v_bcnt_u32_b32 v129, s27, v129
	v_bcnt_u32_b32 v131, s29, v131
	v_bcnt_u32_b32 v133, s31, v133
	v_bcnt_u32_b32 v135, s35, v135
.Lidx_next3:
	s_add_u32 s60, s60, 1
	s_cmp_gt_u32 s60, s61
	s_cbranch_scc1 .Lidx_done
	s_branch .Lidx_loop
.Lidx_diag0:
	v_max_i32_e32 v96, 0, v96
	v_max_i32_e32 v100, 0, v100
	v_max_i32_e32 v104, 0, v104
	v_max_i32_e32 v108, 0, v108
	v_max_i32_e32 v97, 0, v97
	v_max_i32_e32 v101, 0, v101
	v_max_i32_e32 v105, 0, v105
	v_max_i32_e32 v109, 0, v109
	v_mul_f32_e32 v96, v159, v96
	v_mul_f32_e32 v100, v177, v100
	v_mul_f32_e32 v104, v181, v104
	v_mul_f32_e32 v108, v185, v108
	v_max_i32_e32 v98, 0, v98
	v_max_i32_e32 v102, 0, v102
	v_max_i32_e32 v106, 0, v106
	v_max_i32_e32 v110, 0, v110
	v_fmac_f32_e32 v96, v97, v174
	v_fmac_f32_e32 v100, v101, v178
	v_fmac_f32_e32 v104, v105, v182
	v_fmac_f32_e32 v108, v109, v186
	v_max_i32_e32 v99, 0, v99
	v_max_i32_e32 v103, 0, v103
	v_max_i32_e32 v107, 0, v107
	v_max_i32_e32 v111, 0, v111
	v_fmac_f32_e32 v96, v98, v175
	v_fmac_f32_e32 v100, v102, v179
	v_fmac_f32_e32 v104, v106, v183
	v_fmac_f32_e32 v108, v110, v187
	v_fmac_f32_e32 v96, v99, v176
	v_fmac_f32_e32 v100, v103, v180
	v_fmac_f32_e32 v104, v107, v184
	v_fmac_f32_e32 v108, v111, v188
	v_add_f32_e32 v96, 0, v96
	v_add_f32_e32 v100, 0, v100
	v_add_f32_e32 v104, 0, v104
	v_add_f32_e32 v108, 0, v108
	v_ashrrev_i32_e32 v97, 31, v96
	v_ashrrev_i32_e32 v101, 31, v100
	v_ashrrev_i32_e32 v105, 31, v104
	v_ashrrev_i32_e32 v109, 31, v108
	v_bitop3_b32 v96, v97, v96, s81 bitop3:0x36
	v_bitop3_b32 v100, v101, v100, s81 bitop3:0x36
	v_bitop3_b32 v104, v105, v104, s81 bitop3:0x36
	v_bitop3_b32 v108, v109, v108, s81 bitop3:0x36
	v_and_or_b32 v96, v96, s82, v13
	v_and_or_b32 v100, v100, s82, v13
	v_and_or_b32 v104, v104, s82, v13
	v_and_or_b32 v108, v108, s82, v13
	v_cmp_ge_u32_e64 s[26:27], v96, v216
	v_cmp_ge_u32_e64 s[28:29], v100, v218
	v_cmp_ge_u32_e64 s[30:31], v104, v220
	v_cmp_ge_u32_e64 s[34:35], v108, v222
	v_cmp_le_i32_e64 s[36:37], v215, v152
	v_cmp_le_i32_e64 s[38:39], v215, v154
	v_cmp_le_i32_e64 s[40:41], v215, v156
	v_cmp_le_i32_e64 s[2:3], v215, v158
	v_cndmask_b32_e64 v97, v129, v128, s[4:5]
	v_cndmask_b32_e64 v101, v131, v130, s[4:5]
	v_cndmask_b32_e64 v105, v133, v132, s[4:5]
	v_cndmask_b32_e64 v109, v135, v134, s[4:5]
	s_and_b64 s[26:27], s[26:27], s[36:37]
	s_and_b64 s[28:29], s[28:29], s[38:39]
	s_and_b64 s[30:31], s[30:31], s[40:41]
	s_and_b64 s[34:35], s[34:35], s[2:3]
	v_mbcnt_lo_u32_b32 v98, s26, 0
	v_mbcnt_lo_u32_b32 v102, s28, 0
	v_mbcnt_lo_u32_b32 v106, s30, 0
	v_mbcnt_lo_u32_b32 v110, s34, 0
	v_mbcnt_hi_u32_b32 v99, s27, 0
	v_mbcnt_hi_u32_b32 v103, s29, 0
	v_mbcnt_hi_u32_b32 v107, s31, 0
	v_mbcnt_hi_u32_b32 v111, s35, 0
	v_cndmask_b32_e64 v98, v99, v98, s[4:5]
	v_cndmask_b32_e64 v102, v103, v102, s[4:5]
	v_cndmask_b32_e64 v106, v107, v106, s[4:5]
	v_cndmask_b32_e64 v110, v111, v110, s[4:5]
	v_add_u32_e32 v97, v97, v98
	v_add_u32_e32 v101, v101, v102
	v_add_u32_e32 v105, v105, v106
	v_add_u32_e32 v109, v109, v110
	v_lshl_add_u32 v97, v97, 2, v214
	v_lshl_add_u32 v101, v101, 2, v137
	v_lshl_add_u32 v105, v105, 2, v138
	v_lshl_add_u32 v109, v109, 2, v139
	v_cndmask_b32_e64 v97, v136, v97, s[26:27]
	v_cndmask_b32_e64 v101, v136, v101, s[28:29]
	v_cndmask_b32_e64 v105, v136, v105, s[30:31]
	v_cndmask_b32_e64 v109, v136, v109, s[34:35]
	ds_write_b32 v97, v96
	ds_write_b32 v101, v100
	ds_write_b32 v105, v104
	ds_write_b32 v109, v108
	v_bcnt_u32_b32 v128, s26, v128
	v_bcnt_u32_b32 v130, s28, v130
	v_bcnt_u32_b32 v132, s30, v132
	v_bcnt_u32_b32 v134, s34, v134
	v_bcnt_u32_b32 v129, s27, v129
	v_bcnt_u32_b32 v131, s29, v131
	v_bcnt_u32_b32 v133, s31, v133
	v_bcnt_u32_b32 v135, s35, v135
	s_branch .Lidx_next0
.Lidx_diag1:
	v_max_i32_e32 v112, 0, v112
	v_max_i32_e32 v116, 0, v116
	v_max_i32_e32 v120, 0, v120
	v_max_i32_e32 v124, 0, v124
	v_max_i32_e32 v113, 0, v113
	v_max_i32_e32 v117, 0, v117
	v_max_i32_e32 v121, 0, v121
	v_max_i32_e32 v125, 0, v125
	v_mul_f32_e32 v112, v159, v112
	v_mul_f32_e32 v116, v177, v116
	v_mul_f32_e32 v120, v181, v120
	v_mul_f32_e32 v124, v185, v124
	v_max_i32_e32 v114, 0, v114
	v_max_i32_e32 v118, 0, v118
	v_max_i32_e32 v122, 0, v122
	v_max_i32_e32 v126, 0, v126
	v_fmac_f32_e32 v112, v113, v174
	v_fmac_f32_e32 v116, v117, v178
	v_fmac_f32_e32 v120, v121, v182
	v_fmac_f32_e32 v124, v125, v186
	v_max_i32_e32 v115, 0, v115
	v_max_i32_e32 v119, 0, v119
	v_max_i32_e32 v123, 0, v123
	v_max_i32_e32 v127, 0, v127
	v_fmac_f32_e32 v112, v114, v175
	v_fmac_f32_e32 v116, v118, v179
	v_fmac_f32_e32 v120, v122, v183
	v_fmac_f32_e32 v124, v126, v187
	v_fmac_f32_e32 v112, v115, v176
	v_fmac_f32_e32 v116, v119, v180
	v_fmac_f32_e32 v120, v123, v184
	v_fmac_f32_e32 v124, v127, v188
	v_add_f32_e32 v112, 0, v112
	v_add_f32_e32 v116, 0, v116
	v_add_f32_e32 v120, 0, v120
	v_add_f32_e32 v124, 0, v124
	v_ashrrev_i32_e32 v113, 31, v112
	v_ashrrev_i32_e32 v117, 31, v116
	v_ashrrev_i32_e32 v121, 31, v120
	v_ashrrev_i32_e32 v125, 31, v124
	v_bitop3_b32 v112, v113, v112, s81 bitop3:0x36
	v_bitop3_b32 v116, v117, v116, s81 bitop3:0x36
	v_bitop3_b32 v120, v121, v120, s81 bitop3:0x36
	v_bitop3_b32 v124, v125, v124, s81 bitop3:0x36
	v_and_or_b32 v112, v112, s82, v13
	v_and_or_b32 v116, v116, s82, v13
	v_and_or_b32 v120, v120, s82, v13
	v_and_or_b32 v124, v124, s82, v13
	v_cmp_ge_u32_e64 s[26:27], v112, v216
	v_cmp_ge_u32_e64 s[28:29], v116, v218
	v_cmp_ge_u32_e64 s[30:31], v120, v220
	v_cmp_ge_u32_e64 s[34:35], v124, v222
	v_cmp_le_i32_e64 s[36:37], v215, v152
	v_cmp_le_i32_e64 s[38:39], v215, v154
	v_cmp_le_i32_e64 s[40:41], v215, v156
	v_cmp_le_i32_e64 s[2:3], v215, v158
	v_cndmask_b32_e64 v113, v129, v128, s[4:5]
	v_cndmask_b32_e64 v117, v131, v130, s[4:5]
	v_cndmask_b32_e64 v121, v133, v132, s[4:5]
	v_cndmask_b32_e64 v125, v135, v134, s[4:5]
	s_and_b64 s[26:27], s[26:27], s[36:37]
	s_and_b64 s[28:29], s[28:29], s[38:39]
	s_and_b64 s[30:31], s[30:31], s[40:41]
	s_and_b64 s[34:35], s[34:35], s[2:3]
	v_mbcnt_lo_u32_b32 v114, s26, 0
	v_mbcnt_lo_u32_b32 v118, s28, 0
	v_mbcnt_lo_u32_b32 v122, s30, 0
	v_mbcnt_lo_u32_b32 v126, s34, 0
	v_mbcnt_hi_u32_b32 v115, s27, 0
	v_mbcnt_hi_u32_b32 v119, s29, 0
	v_mbcnt_hi_u32_b32 v123, s31, 0
	v_mbcnt_hi_u32_b32 v127, s35, 0
	v_cndmask_b32_e64 v114, v115, v114, s[4:5]
	v_cndmask_b32_e64 v118, v119, v118, s[4:5]
	v_cndmask_b32_e64 v122, v123, v122, s[4:5]
	v_cndmask_b32_e64 v126, v127, v126, s[4:5]
	v_add_u32_e32 v113, v113, v114
	v_add_u32_e32 v117, v117, v118
	v_add_u32_e32 v121, v121, v122
	v_add_u32_e32 v125, v125, v126
	v_lshl_add_u32 v113, v113, 2, v214
	v_lshl_add_u32 v117, v117, 2, v137
	v_lshl_add_u32 v121, v121, 2, v138
	v_lshl_add_u32 v125, v125, 2, v139
	v_cndmask_b32_e64 v113, v136, v113, s[26:27]
	v_cndmask_b32_e64 v117, v136, v117, s[28:29]
	v_cndmask_b32_e64 v121, v136, v121, s[30:31]
	v_cndmask_b32_e64 v125, v136, v125, s[34:35]
	ds_write_b32 v113, v112
	ds_write_b32 v117, v116
	ds_write_b32 v121, v120
	ds_write_b32 v125, v124
	v_bcnt_u32_b32 v128, s26, v128
	v_bcnt_u32_b32 v130, s28, v130
	v_bcnt_u32_b32 v132, s30, v132
	v_bcnt_u32_b32 v134, s34, v134
	v_bcnt_u32_b32 v129, s27, v129
	v_bcnt_u32_b32 v131, s29, v131
	v_bcnt_u32_b32 v133, s31, v133
	v_bcnt_u32_b32 v135, s35, v135
	s_branch .Lidx_next1

.Lidx_compact:
	v_mov_b32_e32 v173, 0
	v_cndmask_b32_e64 v173, v173, v128, s[10:11]
	v_cndmask_b32_e64 v173, v173, v129, s[12:13]
	v_cndmask_b32_e64 v173, v173, v130, s[14:15]
	v_cndmask_b32_e64 v173, v173, v131, s[16:17]
	v_cndmask_b32_e64 v173, v173, v132, s[18:19]
	v_cndmask_b32_e64 v173, v173, v133, s[20:21]
	v_cndmask_b32_e64 v173, v173, v134, s[22:23]
	v_cndmask_b32_e64 v173, v173, v135, s[24:25]
	v_cmp_lt_i32_e32 vcc, s80, v173
	s_and_b64 s[0:1], s[8:9], vcc
	s_branch .LBB0_549
.Lidx_done:
	v_mov_b32_e32 v173, 0
	v_cndmask_b32_e64 v173, v173, v128, s[10:11]
	v_cndmask_b32_e64 v173, v173, v129, s[12:13]
	v_cndmask_b32_e64 v173, v173, v130, s[14:15]
	v_cndmask_b32_e64 v173, v173, v131, s[16:17]
	v_cndmask_b32_e64 v173, v173, v132, s[18:19]
	v_cndmask_b32_e64 v173, v173, v133, s[20:21]
	v_cndmask_b32_e64 v173, v173, v134, s[22:23]
	v_cndmask_b32_e64 v173, v173, v135, s[24:25]
	s_branch .LBB0_1451

.LBB0_549:
	s_ff1_i32_b64 s85, s[0:1]
	v_readlane_b32 s87, v173, s85
	v_lshl_add_u32 v0, s85, 11, v172
	v_mov_b32_e32 v5, 0
	v_cmp_gt_i32_e32 vcc, s87, v151
	v_mov_b32_e32 v8, 0
	s_and_saveexec_b64 s[2:3], vcc
	v_lshl_add_u32 v1, v151, 2, v0
	ds_read_b32 v8, v1
	s_or_b64 exec, exec, s[2:3]
	v_cmp_gt_i32_e32 vcc, s87, v192
	s_and_saveexec_b64 s[2:3], vcc
	v_lshl_add_u32 v1, v151, 2, v0
	ds_read_b32 v5, v1 offset:256
	s_or_b64 exec, exec, s[2:3]
	v_cmp_gt_i32_e32 vcc, s87, v193
	v_mov_b32_e32 v3, 0
	v_mov_b32_e32 v7, 0
	s_and_saveexec_b64 s[2:3], vcc
	v_lshl_add_u32 v1, v151, 2, v0
	ds_read_b32 v7, v1 offset:512
	s_or_b64 exec, exec, s[2:3]
	v_cmp_gt_i32_e32 vcc, s87, v194
	s_and_saveexec_b64 s[2:3], vcc
	v_lshl_add_u32 v1, v151, 2, v0
	ds_read_b32 v3, v1 offset:768
	s_or_b64 exec, exec, s[2:3]
	v_cmp_gt_i32_e32 vcc, s87, v195
	v_mov_b32_e32 v2, 0
	v_mov_b32_e32 v6, 0
	s_and_saveexec_b64 s[2:3], vcc
	v_lshl_add_u32 v1, v151, 2, v0
	ds_read_b32 v6, v1 offset:1024
	s_or_b64 exec, exec, s[2:3]
	v_cmp_gt_i32_e32 vcc, s87, v196
	s_and_saveexec_b64 s[2:3], vcc
	v_lshl_add_u32 v1, v151, 2, v0
	ds_read_b32 v2, v1 offset:1280
	s_or_b64 exec, exec, s[2:3]
	v_cmp_gt_i32_e32 vcc, s87, v197
	v_mov_b32_e32 v1, 0
	v_mov_b32_e32 v4, 0
	s_and_saveexec_b64 s[2:3], vcc
	v_lshl_add_u32 v4, v151, 2, v0
	ds_read_b32 v4, v4 offset:1536
	s_or_b64 exec, exec, s[2:3]
	v_cmp_gt_i32_e32 vcc, s87, v213
	s_and_saveexec_b64 s[2:3], vcc
	v_lshl_add_u32 v1, v151, 2, v0
	ds_read_b32 v1, v1 offset:1792
	s_or_b64 exec, exec, s[2:3]
	s_waitcnt lgkmcnt(0)
	v_max3_u32 v9, v8, v5, v7
	v_max3_u32 v9, v9, v3, v6
	v_max3_u32 v9, v9, v2, v4
	v_max_u32_e32 v9, v9, v1
	v_min3_u32 v10, v8, v5, v7
	v_min3_u32 v10, v10, v3, v6
	v_min3_u32 v10, v10, v2, v4
	v_cmp_ne_u32_e64 s[38:39], 0, v1
	v_mov_b32_e32 v140, 0
	v_mov_b32_e32 v141, 0
	v_mov_b32_e32 v142, 0
	v_mov_b32_e32 v143, 0
	v_cndmask_b32_e64 v12, -1, v1, s[38:39]
	v_min_u32_e32 v10, v10, v12
	v_lshl_add_u32 v198, v151, 4, v224
	ds_write_b128 v198, v[140:143] offset:1024
	s_nop 1
	v_max_u32_dpp v9, v9, v9 row_ror:8 row_mask:0xf bank_mask:0xf
	v_min_u32_dpp v10, v10, v10 row_ror:8 row_mask:0xf bank_mask:0xf
	s_nop 1
	v_max_u32_dpp v9, v9, v9 row_ror:4 row_mask:0xf bank_mask:0xf
	v_min_u32_dpp v10, v10, v10 row_ror:4 row_mask:0xf bank_mask:0xf
	s_nop 1
	v_max_u32_dpp v9, v9, v9 row_ror:2 row_mask:0xf bank_mask:0xf
	v_min_u32_dpp v10, v10, v10 row_ror:2 row_mask:0xf bank_mask:0xf
	s_nop 1
	v_max_u32_dpp v9, v9, v9 row_ror:1 row_mask:0xf bank_mask:0xf
	v_min_u32_dpp v10, v10, v10 row_ror:1 row_mask:0xf bank_mask:0xf
	s_nop 1
	v_readlane_b32 s26, v10, 0
	v_readlane_b32 s28, v10, 16
	v_readlane_b32 s30, v10, 32
	v_readlane_b32 s31, v10, 48
	v_readlane_b32 s27, v9, 0
	v_readlane_b32 s34, v9, 16
	v_readlane_b32 s35, v9, 32
	v_readlane_b32 s36, v9, 48
	s_min_u32 s26, s26, s28
	s_min_u32 s30, s30, s31
	s_min_u32 s26, s26, s30
	s_max_u32 s27, s27, s34
	s_max_u32 s35, s35, s36
	s_max_u32 s27, s27, s35
	v_mov_b32_e32 v15, 1
	s_sub_u32 s28, s27, s26
	s_flbit_i32_b32 s29, s28
	s_sub_i32 s29, 24, s29
	s_max_i32 s29, s29, 0
	v_subrev_u32_e32 v12, s26, v8
	v_lshrrev_b32_e32 v12, s29, v12
	v_lshl_add_u32 v12, v12, 2, v224
	ds_add_u32 v12, v15 offset:1024
	v_subrev_u32_e32 v9, s26, v5
	v_lshrrev_b32_e32 v9, s29, v9
	v_lshl_add_u32 v9, v9, 2, v224
	ds_add_u32 v9, v15 offset:1024
	v_subrev_u32_e32 v12, s26, v7
	v_lshrrev_b32_e32 v12, s29, v12
	v_lshl_add_u32 v12, v12, 2, v224
	ds_add_u32 v12, v15 offset:1024
	v_subrev_u32_e32 v9, s26, v3
	v_lshrrev_b32_e32 v9, s29, v9
	v_lshl_add_u32 v9, v9, 2, v224
	ds_add_u32 v9, v15 offset:1024
	v_subrev_u32_e32 v12, s26, v6
	v_lshrrev_b32_e32 v12, s29, v12
	v_lshl_add_u32 v12, v12, 2, v224
	ds_add_u32 v12, v15 offset:1024
	v_subrev_u32_e32 v9, s26, v2
	v_lshrrev_b32_e32 v9, s29, v9
	v_lshl_add_u32 v9, v9, 2, v224
	ds_add_u32 v9, v15 offset:1024
	v_subrev_u32_e32 v12, s26, v4
	v_lshrrev_b32_e32 v12, s29, v12
	v_lshl_add_u32 v12, v12, 2, v224
	ds_add_u32 v12, v15 offset:1024
	v_subrev_u32_e32 v9, s26, v1
	v_lshrrev_b32_e32 v9, s29, v9
	v_lshl_add_u32 v9, v9, 2, v224
	v_add_u32_e32 v10, 0x400, v136
	v_cndmask_b32_e64 v9, v10, v9, s[38:39]
	ds_add_u32 v9, v15 offset:1024
	ds_read_b128 v[140:143], v198 offset:1024
	s_movk_i32 s90, 0x100
	s_mov_b64 s[36:37], 0xffff
	s_mov_b32 s40, -1
	s_mov_b32 s41, 0xffff
	s_waitcnt lgkmcnt(0)
	v_add_u32_e32 v142, v142, v143
	v_add_u32_e32 v141, v141, v142
	v_add_u32_e32 v140, v140, v141
	v_mov_b32_e32 v15, v140
	s_nop 1
	v_add_u32_dpp v15, v15, v15 row_shl:1 row_mask:0xf bank_mask:0xf bound_ctrl:0
	s_nop 1
	v_add_u32_dpp v15, v15, v15 row_shl:2 row_mask:0xf bank_mask:0xf bound_ctrl:0
	s_nop 1
	v_add_u32_dpp v15, v15, v15 row_shl:4 row_mask:0xf bank_mask:0xf bound_ctrl:0
	s_nop 1
	v_add_u32_dpp v15, v15, v15 row_shl:8 row_mask:0xf bank_mask:0xf bound_ctrl:0
	s_nop 1
	v_readlane_b32 s30, v15, 16
	v_readlane_b32 s31, v15, 32
	v_readlane_b32 s34, v15, 48
	v_mov_b32_e32 v12, 0
	s_add_u32 s35, s31, s34
	s_add_u32 s89, s30, s35
	v_mov_b32_e32 v9, s34
	v_mov_b32_e32 v10, s35
	v_mov_b32_e32 v14, s89
	v_cndmask_b32_e64 v12, v12, v9, s[40:41]
	v_cndmask_b32_e64 v12, v12, v10, s[4:5]
	v_cndmask_b32_e64 v12, v12, v14, s[36:37]
	v_add_u32_e32 v15, v15, v12
	v_cmp_le_u32_e32 vcc, s90, v15
	v_sub_u32_e32 v12, v15, v140
	s_flbit_i32_b64 s91, vcc
	s_sub_u32 s91, 63, s91
	v_add_u32_e32 v141, v12, v141
	v_add_u32_e32 v142, v12, v142
	v_add_u32_e32 v143, v12, v143
	v_mov_b32_e32 v9, v15
	v_cmp_le_u32_e32 vcc, s90, v141
	s_nop 1
	v_cndmask_b32_e64 v198, 0, 1, vcc
	v_cndmask_b32_e32 v9, v9, v141, vcc
	v_cmp_le_u32_e32 vcc, s90, v142
	s_nop 1
	v_cndmask_b32_e32 v9, v9, v142, vcc
	v_addc_co_u32_e32 v198, vcc, 0, v198, vcc
	v_cmp_le_u32_e32 vcc, s90, v143
	s_nop 1
	v_cndmask_b32_e32 v9, v9, v143, vcc
	v_addc_co_u32_e32 v198, vcc, 0, v198, vcc
	s_nop 1
	v_readlane_b32 s92, v198, s91
	v_readlane_b32 s89, v9, s91
	s_lshl_b32 s93, s91, 2
	s_add_u32 s93, s93, s92
	s_lshl_b32 s93, s93, s29
	s_add_u32 s88, s26, s93
	s_cmpk_gt_u32 s89, 0x180
	s_cbranch_scc0 .LBB0_600
.Lidx_bitsearch:
	s_mov_b32 s89, 1
	s_cmp_lt_i32 s89, 1
	s_cbranch_scc1 .LBB0_597
	s_waitcnt lgkmcnt(0)
	v_cmp_gt_i32_e32 vcc, 0, v8
	v_cmp_gt_i32_e64 s[2:3], 0, v5
	v_cmp_gt_i32_e64 s[26:27], 0, v7
	v_cmp_gt_i32_e64 s[28:29], 0, v3
	v_cmp_gt_i32_e64 s[30:31], 0, v6
	v_cmp_gt_i32_e64 s[34:35], 0, v2
	v_cmp_gt_i32_e64 s[36:37], 0, v4
	v_cmp_gt_i32_e64 s[38:39], 0, v1
	s_branch .LBB0_568

.LBB0_616:
	v_readlane_b32 s0, v144, 0
	v_readlane_b32 s1, v144, 1
	s_nop 0
	v_mov_b32_e32 v1, s0
	v_mov_b32_e32 v0, s1
	v_cndmask_b32_e64 v216, v0, v1, s[4:5]
	v_cmp_lt_i32_e32 vcc, -1, v216
	v_readlane_b32 s0, v144, 2
	v_readlane_b32 s1, v144, 3
	v_cndmask_b32_e64 v0, v207, -1, vcc
	v_bitop3_b32 v0, v0, v216, s82 bitop3:0x78
	v_cmp_ne_u32_e32 vcc, 0, v216
	v_mov_b32_e32 v1, s0
	v_readlane_b32 s0, v144, 4
	v_cndmask_b32_e32 v217, v208, v0, vcc
	v_mov_b32_e32 v0, s1
	v_cndmask_b32_e64 v218, v0, v1, s[4:5]
	v_cmp_lt_i32_e32 vcc, -1, v218
	v_readlane_b32 s1, v144, 5
	v_mov_b32_e32 v1, s0
	v_cndmask_b32_e64 v0, v207, -1, vcc
	v_bitop3_b32 v0, v0, v218, s82 bitop3:0x78
	v_cmp_ne_u32_e32 vcc, 0, v218
	v_readlane_b32 s0, v144, 6
	s_nop 0
	v_cndmask_b32_e32 v219, v208, v0, vcc
	v_mov_b32_e32 v0, s1
	v_cndmask_b32_e64 v220, v0, v1, s[4:5]
	v_cmp_lt_i32_e32 vcc, -1, v220
	v_readlane_b32 s1, v144, 7
	v_mov_b32_e32 v1, s0
	v_cndmask_b32_e64 v0, v207, -1, vcc
	v_bitop3_b32 v0, v0, v220, s82 bitop3:0x78
	v_cmp_ne_u32_e32 vcc, 0, v220
	s_nop 1
	v_cndmask_b32_e32 v221, v208, v0, vcc
	v_mov_b32_e32 v0, s1
	v_cndmask_b32_e64 v222, v0, v1, s[4:5]
	v_cmp_lt_i32_e32 vcc, -1, v222
	s_nop 1
	v_cndmask_b32_e64 v0, v207, -1, vcc
	v_bitop3_b32 v0, v0, v222, s82 bitop3:0x78
	v_cmp_ne_u32_e32 vcc, 0, v222
	s_nop 1
	v_cndmask_b32_e32 v223, v208, v0, vcc
	s_nop 1
	v_readlane_b32 s26, v173, 0
	v_readlane_b32 s27, v173, 1
	v_readlane_b32 s28, v173, 2
	v_readlane_b32 s29, v173, 3
	v_readlane_b32 s30, v173, 4
	v_readlane_b32 s31, v173, 5
	v_readlane_b32 s34, v173, 6
	v_readlane_b32 s35, v173, 7
	s_nop 1
	v_mov_b32_e32 v128, s26
	v_mov_b32_e32 v129, s27
	v_mov_b32_e32 v130, s28
	v_mov_b32_e32 v131, s29
	v_mov_b32_e32 v132, s30
	v_mov_b32_e32 v133, s31
	v_mov_b32_e32 v134, s34
	v_mov_b32_e32 v135, s35
	s_cmp_eq_u32 s67, 0
	s_cbranch_scc1 .Lidx_resume0
	s_cmp_eq_u32 s67, 1
	s_cbranch_scc1 .Lidx_resume1
	s_cmp_eq_u32 s67, 2
	s_cbranch_scc1 .Lidx_resume2
	s_branch .Lidx_resume3
